# EpiRes epilogue store sites: bf16 path falls through one not-taken branch, f32 store out of line
# baseline (speedup 1.0000x reference)
.Ler_f0:
	v_lshlrev_b32_e32 v150, 2, v145
	s_mov_b64 s[12:13], 0
	buffer_store_dwordx4 v[120:123], v150, s[28:31], 0 offen sc1
	s_branch .LBB0_614
.Ler_f1:
	v_lshlrev_b32_e32 v150, 2, v145
	s_mov_b64 s[12:13], 0
	buffer_store_dwordx4 v[116:119], v150, s[28:31], 0 offen sc1
	s_branch .LBB0_618
.Ler_f2:
	v_lshlrev_b32_e32 v145, 2, v144
	s_mov_b64 s[12:13], 0
	buffer_store_dwordx4 v[112:115], v145, s[28:31], 0 offen sc1
	s_branch .LBB0_622
.Ler_f3:
	v_lshlrev_b32_e32 v115, 2, v114
	s_mov_b64 s[72:73], 0
	buffer_store_dwordx4 v[108:111], v115, s[28:31], 0 offen sc1
	s_branch .LBB0_630
.Ler_f4:
	v_lshlrev_b32_e32 v116, 2, v115
	s_mov_b64 s[72:73], 0
	buffer_store_dwordx4 v[104:107], v116, s[28:31], 0 offen sc1
	s_branch .LBB0_634
.Ler_f5:
	v_lshlrev_b32_e32 v116, 2, v115
	s_mov_b64 s[72:73], 0
	buffer_store_dwordx4 v[100:103], v116, s[28:31], 0 offen sc1
	s_branch .LBB0_638
.Ler_f6:
	v_lshlrev_b32_e32 v99, 2, v98
	s_mov_b64 s[72:73], 0
	buffer_store_dwordx4 v[92:95], v99, s[28:31], 0 offen sc1
	s_branch .LBB0_650
.Ler_f7:
	v_lshlrev_b32_e32 v100, 2, v99
	s_mov_b64 s[72:73], 0
	buffer_store_dwordx4 v[88:91], v100, s[28:31], 0 offen sc1
	s_branch .LBB0_654
.Ler_f8:
	v_lshlrev_b32_e32 v100, 2, v99
	s_mov_b64 s[72:73], 0
	buffer_store_dwordx4 v[84:87], v100, s[28:31], 0 offen sc1
	s_branch .LBB0_658
.Ler_f9:
	v_lshlrev_b32_e32 v83, 2, v82
	s_mov_b64 s[72:73], 0
	buffer_store_dwordx4 v[76:79], v83, s[28:31], 0 offen sc1
	s_branch .LBB0_670
.Ler_f10:
	v_lshlrev_b32_e32 v84, 2, v83
	s_mov_b64 s[72:73], 0
	buffer_store_dwordx4 v[72:75], v84, s[28:31], 0 offen sc1
	s_branch .LBB0_674
.Ler_f11:
	v_lshlrev_b32_e32 v84, 2, v83
	s_mov_b64 s[72:73], 0
	buffer_store_dwordx4 v[68:71], v84, s[28:31], 0 offen sc1
	s_branch .LBB0_678
.Ler_f12:
	v_lshlrev_b32_e32 v67, 2, v66
	s_mov_b64 s[72:73], 0
	buffer_store_dwordx4 v[60:63], v67, s[28:31], 0 offen sc1
	s_branch .LBB0_690
.Ler_f13:
	v_lshlrev_b32_e32 v68, 2, v67
	s_mov_b64 s[72:73], 0
	buffer_store_dwordx4 v[56:59], v68, s[28:31], 0 offen sc1
	s_branch .LBB0_694
.Ler_f14:
	v_lshlrev_b32_e32 v68, 2, v67
	s_mov_b64 s[72:73], 0
	buffer_store_dwordx4 v[52:55], v68, s[28:31], 0 offen sc1
	s_branch .LBB0_698
.Ler_f15:
	v_lshlrev_b32_e32 v51, 2, v50
	s_mov_b64 s[72:73], 0
	buffer_store_dwordx4 v[44:47], v51, s[28:31], 0 offen sc1
	s_branch .LBB0_710
.Ler_f16:
	v_lshlrev_b32_e32 v52, 2, v51
	s_mov_b64 s[72:73], 0
	buffer_store_dwordx4 v[40:43], v52, s[28:31], 0 offen sc1
	s_branch .LBB0_714
.Ler_f17:
	v_lshlrev_b32_e32 v52, 2, v51
	s_mov_b64 s[72:73], 0
	buffer_store_dwordx4 v[36:39], v52, s[28:31], 0 offen sc1
	s_branch .LBB0_718
.Ler_f18:
	v_lshlrev_b32_e32 v35, 2, v34
	s_mov_b64 s[72:73], 0
	buffer_store_dwordx4 v[28:31], v35, s[28:31], 0 offen sc1
	s_branch .LBB0_730
.Ler_f19:
	v_lshlrev_b32_e32 v36, 2, v35
	s_mov_b64 s[72:73], 0
	buffer_store_dwordx4 v[24:27], v36, s[28:31], 0 offen sc1
	s_branch .LBB0_734
.Ler_f20:
	v_lshlrev_b32_e32 v36, 2, v35
	s_mov_b64 s[72:73], 0
	buffer_store_dwordx4 v[20:23], v36, s[28:31], 0 offen sc1
	s_branch .LBB0_738
.Ler_f21:
	v_lshlrev_b32_e32 v19, 2, v18
	s_mov_b64 s[72:73], 0
	buffer_store_dwordx4 v[12:15], v19, s[28:31], 0 offen sc1
	s_branch .LBB0_750
.Ler_f22:
	v_lshlrev_b32_e32 v20, 2, v19
	s_mov_b64 s[72:73], 0
	buffer_store_dwordx4 v[8:11], v20, s[28:31], 0 offen sc1
	s_branch .LBB0_754
.Ler_f23:
	v_lshlrev_b32_e32 v20, 2, v19
	s_mov_b64 s[72:73], 0
	buffer_store_dwordx4 v[4:7], v20, s[28:31], 0 offen sc1
	s_branch .LBB0_758

.LBB0_610:
	v_or_b32_e32 v145, 16, v144
	v_pk_mul_f32 v[122:123], s[18:19], v[122:123]
	v_pk_mul_f32 v[120:121], s[16:17], v[120:121]
	s_andn2_b64 vcc, exec, s[10:11]
	s_mov_b64 s[12:13], -1
	s_cbranch_vccnz .Ler_f0
	v_cvt_pk_bf16_f32 v252, v120, v121
	v_cvt_pk_bf16_f32 v253, v122, v123
	v_and_b32_e32 v150, 16, v197
	v_lshrrev_b32_e32 v151, 1, v150
	v_add3_u32 v254, v254, v150, v151
	v_permlane16_swap_b32_e32 v250, v252
	v_permlane16_swap_b32_e32 v251, v253
	buffer_store_dwordx4 v[250:253], v254, s[24:27], 0 offen sc1
.LBB0_614:
	v_or_b32_e32 v145, 0x80, v144
	v_pk_mul_f32 v[118:119], s[18:19], v[118:119]
	v_pk_mul_f32 v[116:117], s[16:17], v[116:117]
	s_andn2_b64 vcc, exec, s[10:11]
	s_mov_b64 s[12:13], -1
	s_cbranch_vccnz .Ler_f1
	v_lshlrev_b32_e32 v254, 1, v145
	v_cvt_pk_bf16_f32 v250, v116, v117
	v_cvt_pk_bf16_f32 v251, v118, v119
.LBB0_618:
	v_or_b32_e32 v144, 0x90, v144
	v_pk_mul_f32 v[114:115], s[18:19], v[114:115]
	v_pk_mul_f32 v[112:113], s[16:17], v[112:113]
	s_andn2_b64 vcc, exec, s[10:11]
	s_mov_b64 s[12:13], -1
	s_cbranch_vccnz .Ler_f2
	v_cvt_pk_bf16_f32 v252, v112, v113
	v_cvt_pk_bf16_f32 v253, v114, v115
	v_and_b32_e32 v150, 16, v197
	v_lshrrev_b32_e32 v151, 1, v150
	v_add3_u32 v254, v254, v150, v151
	v_permlane16_swap_b32_e32 v250, v252
	v_permlane16_swap_b32_e32 v251, v253
	buffer_store_dwordx4 v[250:253], v254, s[24:27], 0 offen sc1

.LBB0_626:
	v_or_b32_e32 v112, 16, v142
	s_waitcnt lgkmcnt(0)
	v_ashrrev_i32_e32 v113, 31, v112
	v_lshlrev_b64 v[114:115], 10, v[112:113]
	v_lshl_add_u64 v[114:115], v[114:115], 0, v[158:159]
	v_pk_mul_f32 v[110:111], s[18:19], v[110:111]
	v_pk_mul_f32 v[108:109], s[16:17], v[108:109]
	s_andn2_b64 vcc, exec, s[10:11]
	s_mov_b64 s[72:73], -1
	s_cbranch_vccnz .Ler_f3
	v_lshlrev_b32_e32 v254, 1, v114
	v_cvt_pk_bf16_f32 v250, v108, v109
	v_cvt_pk_bf16_f32 v251, v110, v111
.LBB0_630:
	v_or_b32_e32 v115, 16, v114
	v_pk_mul_f32 v[106:107], s[18:19], v[106:107]
	v_pk_mul_f32 v[104:105], s[16:17], v[104:105]
	s_andn2_b64 vcc, exec, s[10:11]
	s_mov_b64 s[72:73], -1
	s_cbranch_vccnz .Ler_f4
	v_cvt_pk_bf16_f32 v252, v104, v105
	v_cvt_pk_bf16_f32 v253, v106, v107
	v_and_b32_e32 v116, 16, v197
	v_lshrrev_b32_e32 v117, 1, v116
	v_add3_u32 v254, v254, v116, v117
	v_permlane16_swap_b32_e32 v250, v252
	v_permlane16_swap_b32_e32 v251, v253
	buffer_store_dwordx4 v[250:253], v254, s[24:27], 0 offen sc1
.LBB0_634:
	v_or_b32_e32 v115, 0x80, v114
	v_pk_mul_f32 v[102:103], s[18:19], v[102:103]
	v_pk_mul_f32 v[100:101], s[16:17], v[100:101]
	s_andn2_b64 vcc, exec, s[10:11]
	s_mov_b64 s[72:73], -1
	s_cbranch_vccnz .Ler_f5
	v_lshlrev_b32_e32 v254, 1, v115
	v_cvt_pk_bf16_f32 v250, v100, v101
	v_cvt_pk_bf16_f32 v251, v102, v103

.LBB0_646:
	v_or_b32_e32 v96, 32, v142
	s_waitcnt lgkmcnt(0)
	v_ashrrev_i32_e32 v97, 31, v96
	v_lshlrev_b64 v[98:99], 10, v[96:97]
	v_lshl_add_u64 v[98:99], v[98:99], 0, v[158:159]
	v_pk_mul_f32 v[94:95], s[18:19], v[94:95]
	v_pk_mul_f32 v[92:93], s[16:17], v[92:93]
	s_andn2_b64 vcc, exec, s[10:11]
	s_mov_b64 s[72:73], -1
	s_cbranch_vccnz .Ler_f6
	v_lshlrev_b32_e32 v254, 1, v98
	v_cvt_pk_bf16_f32 v250, v92, v93
	v_cvt_pk_bf16_f32 v251, v94, v95
.LBB0_650:
	v_or_b32_e32 v99, 16, v98
	v_pk_mul_f32 v[90:91], s[18:19], v[90:91]
	v_pk_mul_f32 v[88:89], s[16:17], v[88:89]
	s_andn2_b64 vcc, exec, s[10:11]
	s_mov_b64 s[72:73], -1
	s_cbranch_vccnz .Ler_f7
	v_cvt_pk_bf16_f32 v252, v88, v89
	v_cvt_pk_bf16_f32 v253, v90, v91
	v_and_b32_e32 v100, 16, v197
	v_lshrrev_b32_e32 v101, 1, v100
	v_add3_u32 v254, v254, v100, v101
	v_permlane16_swap_b32_e32 v250, v252
	v_permlane16_swap_b32_e32 v251, v253
	buffer_store_dwordx4 v[250:253], v254, s[24:27], 0 offen sc1
.LBB0_654:
	v_or_b32_e32 v99, 0x80, v98
	v_pk_mul_f32 v[86:87], s[18:19], v[86:87]
	v_pk_mul_f32 v[84:85], s[16:17], v[84:85]
	s_andn2_b64 vcc, exec, s[10:11]
	s_mov_b64 s[72:73], -1
	s_cbranch_vccnz .Ler_f8
	v_lshlrev_b32_e32 v254, 1, v99
	v_cvt_pk_bf16_f32 v250, v84, v85
	v_cvt_pk_bf16_f32 v251, v86, v87

.LBB0_666:
	v_or_b32_e32 v80, 48, v142
	s_waitcnt lgkmcnt(0)
	v_ashrrev_i32_e32 v81, 31, v80
	v_lshlrev_b64 v[82:83], 10, v[80:81]
	v_lshl_add_u64 v[82:83], v[82:83], 0, v[158:159]
	v_pk_mul_f32 v[78:79], s[18:19], v[78:79]
	v_pk_mul_f32 v[76:77], s[16:17], v[76:77]
	s_andn2_b64 vcc, exec, s[10:11]
	s_mov_b64 s[72:73], -1
	s_cbranch_vccnz .Ler_f9
	v_lshlrev_b32_e32 v254, 1, v82
	v_cvt_pk_bf16_f32 v250, v76, v77
	v_cvt_pk_bf16_f32 v251, v78, v79
.LBB0_670:
	v_or_b32_e32 v83, 16, v82
	v_pk_mul_f32 v[74:75], s[18:19], v[74:75]
	v_pk_mul_f32 v[72:73], s[16:17], v[72:73]
	s_andn2_b64 vcc, exec, s[10:11]
	s_mov_b64 s[72:73], -1
	s_cbranch_vccnz .Ler_f10
	v_cvt_pk_bf16_f32 v252, v72, v73
	v_cvt_pk_bf16_f32 v253, v74, v75
	v_and_b32_e32 v84, 16, v197
	v_lshrrev_b32_e32 v85, 1, v84
	v_add3_u32 v254, v254, v84, v85
	v_permlane16_swap_b32_e32 v250, v252
	v_permlane16_swap_b32_e32 v251, v253
	buffer_store_dwordx4 v[250:253], v254, s[24:27], 0 offen sc1
.LBB0_674:
	v_or_b32_e32 v83, 0x80, v82
	v_pk_mul_f32 v[70:71], s[18:19], v[70:71]
	v_pk_mul_f32 v[68:69], s[16:17], v[68:69]
	s_andn2_b64 vcc, exec, s[10:11]
	s_mov_b64 s[72:73], -1
	s_cbranch_vccnz .Ler_f11
	v_lshlrev_b32_e32 v254, 1, v83
	v_cvt_pk_bf16_f32 v250, v68, v69
	v_cvt_pk_bf16_f32 v251, v70, v71

.LBB0_686:
	v_add_u32_e32 v64, 0x80, v142
	s_waitcnt lgkmcnt(0)
	v_ashrrev_i32_e32 v65, 31, v64
	v_lshlrev_b64 v[66:67], 10, v[64:65]
	v_lshl_add_u64 v[66:67], v[66:67], 0, v[158:159]
	v_pk_mul_f32 v[62:63], s[18:19], v[62:63]
	v_pk_mul_f32 v[60:61], s[16:17], v[60:61]
	s_andn2_b64 vcc, exec, s[10:11]
	s_mov_b64 s[72:73], -1
	s_cbranch_vccnz .Ler_f12
	v_lshlrev_b32_e32 v254, 1, v66
	v_cvt_pk_bf16_f32 v250, v60, v61
	v_cvt_pk_bf16_f32 v251, v62, v63
.LBB0_690:
	v_or_b32_e32 v67, 16, v66
	v_pk_mul_f32 v[58:59], s[18:19], v[58:59]
	v_pk_mul_f32 v[56:57], s[16:17], v[56:57]
	s_andn2_b64 vcc, exec, s[10:11]
	s_mov_b64 s[72:73], -1
	s_cbranch_vccnz .Ler_f13
	v_cvt_pk_bf16_f32 v252, v56, v57
	v_cvt_pk_bf16_f32 v253, v58, v59
	v_and_b32_e32 v68, 16, v197
	v_lshrrev_b32_e32 v69, 1, v68
	v_add3_u32 v254, v254, v68, v69
	v_permlane16_swap_b32_e32 v250, v252
	v_permlane16_swap_b32_e32 v251, v253
	buffer_store_dwordx4 v[250:253], v254, s[24:27], 0 offen sc1
.LBB0_694:
	v_or_b32_e32 v67, 0x80, v66
	v_pk_mul_f32 v[54:55], s[18:19], v[54:55]
	v_pk_mul_f32 v[52:53], s[16:17], v[52:53]
	s_andn2_b64 vcc, exec, s[10:11]
	s_mov_b64 s[72:73], -1
	s_cbranch_vccnz .Ler_f14
	v_lshlrev_b32_e32 v254, 1, v67
	v_cvt_pk_bf16_f32 v250, v52, v53
	v_cvt_pk_bf16_f32 v251, v54, v55

.LBB0_706:
	v_add_u32_e32 v48, 0x90, v142
	s_waitcnt lgkmcnt(0)
	v_ashrrev_i32_e32 v49, 31, v48
	v_lshlrev_b64 v[50:51], 10, v[48:49]
	v_lshl_add_u64 v[50:51], v[50:51], 0, v[158:159]
	v_pk_mul_f32 v[46:47], s[18:19], v[46:47]
	v_pk_mul_f32 v[44:45], s[16:17], v[44:45]
	s_andn2_b64 vcc, exec, s[10:11]
	s_mov_b64 s[72:73], -1
	s_cbranch_vccnz .Ler_f15
	v_lshlrev_b32_e32 v254, 1, v50
	v_cvt_pk_bf16_f32 v250, v44, v45
	v_cvt_pk_bf16_f32 v251, v46, v47
.LBB0_710:
	v_or_b32_e32 v51, 16, v50
	v_pk_mul_f32 v[42:43], s[18:19], v[42:43]
	v_pk_mul_f32 v[40:41], s[16:17], v[40:41]
	s_andn2_b64 vcc, exec, s[10:11]
	s_mov_b64 s[72:73], -1
	s_cbranch_vccnz .Ler_f16
	v_cvt_pk_bf16_f32 v252, v40, v41
	v_cvt_pk_bf16_f32 v253, v42, v43
	v_and_b32_e32 v52, 16, v197
	v_lshrrev_b32_e32 v53, 1, v52
	v_add3_u32 v254, v254, v52, v53
	v_permlane16_swap_b32_e32 v250, v252
	v_permlane16_swap_b32_e32 v251, v253
	buffer_store_dwordx4 v[250:253], v254, s[24:27], 0 offen sc1
.LBB0_714:
	v_or_b32_e32 v51, 0x80, v50
	v_pk_mul_f32 v[38:39], s[18:19], v[38:39]
	v_pk_mul_f32 v[36:37], s[16:17], v[36:37]
	s_andn2_b64 vcc, exec, s[10:11]
	s_mov_b64 s[72:73], -1
	s_cbranch_vccnz .Ler_f17
	v_lshlrev_b32_e32 v254, 1, v51
	v_cvt_pk_bf16_f32 v250, v36, v37
	v_cvt_pk_bf16_f32 v251, v38, v39

.LBB0_726:
	v_add_u32_e32 v32, 0xa0, v142
	s_waitcnt lgkmcnt(0)
	v_ashrrev_i32_e32 v33, 31, v32
	v_lshlrev_b64 v[34:35], 10, v[32:33]
	v_lshl_add_u64 v[34:35], v[34:35], 0, v[158:159]
	v_pk_mul_f32 v[30:31], s[18:19], v[30:31]
	v_pk_mul_f32 v[28:29], s[16:17], v[28:29]
	s_andn2_b64 vcc, exec, s[10:11]
	s_mov_b64 s[72:73], -1
	s_cbranch_vccnz .Ler_f18
	v_lshlrev_b32_e32 v254, 1, v34
	v_cvt_pk_bf16_f32 v250, v28, v29
	v_cvt_pk_bf16_f32 v251, v30, v31
.LBB0_730:
	v_or_b32_e32 v35, 16, v34
	v_pk_mul_f32 v[26:27], s[18:19], v[26:27]
	v_pk_mul_f32 v[24:25], s[16:17], v[24:25]
	s_andn2_b64 vcc, exec, s[10:11]
	s_mov_b64 s[72:73], -1
	s_cbranch_vccnz .Ler_f19
	v_cvt_pk_bf16_f32 v252, v24, v25
	v_cvt_pk_bf16_f32 v253, v26, v27
	v_and_b32_e32 v36, 16, v197
	v_lshrrev_b32_e32 v37, 1, v36
	v_add3_u32 v254, v254, v36, v37
	v_permlane16_swap_b32_e32 v250, v252
	v_permlane16_swap_b32_e32 v251, v253
	buffer_store_dwordx4 v[250:253], v254, s[24:27], 0 offen sc1
.LBB0_734:
	v_or_b32_e32 v35, 0x80, v34
	v_pk_mul_f32 v[22:23], s[18:19], v[22:23]
	v_pk_mul_f32 v[20:21], s[16:17], v[20:21]
	s_andn2_b64 vcc, exec, s[10:11]
	s_mov_b64 s[72:73], -1
	s_cbranch_vccnz .Ler_f20
	v_lshlrev_b32_e32 v254, 1, v35
	v_cvt_pk_bf16_f32 v250, v20, v21
	v_cvt_pk_bf16_f32 v251, v22, v23

.LBB0_746:
	v_add_u32_e32 v16, 0xb0, v142
	s_waitcnt lgkmcnt(0)
	v_ashrrev_i32_e32 v17, 31, v16
	v_lshlrev_b64 v[18:19], 10, v[16:17]
	v_lshl_add_u64 v[18:19], v[18:19], 0, v[158:159]
	v_pk_mul_f32 v[14:15], s[18:19], v[14:15]
	v_pk_mul_f32 v[12:13], s[16:17], v[12:13]
	s_andn2_b64 vcc, exec, s[10:11]
	s_mov_b64 s[72:73], -1
	s_cbranch_vccnz .Ler_f21
	v_lshlrev_b32_e32 v254, 1, v18
	v_cvt_pk_bf16_f32 v250, v12, v13
	v_cvt_pk_bf16_f32 v251, v14, v15
.LBB0_750:
	v_or_b32_e32 v19, 16, v18
	v_pk_mul_f32 v[10:11], s[18:19], v[10:11]
	v_pk_mul_f32 v[8:9], s[16:17], v[8:9]
	s_andn2_b64 vcc, exec, s[10:11]
	s_mov_b64 s[72:73], -1
	s_cbranch_vccnz .Ler_f22
	v_cvt_pk_bf16_f32 v252, v8, v9
	v_cvt_pk_bf16_f32 v253, v10, v11
	v_and_b32_e32 v20, 16, v197
	v_lshrrev_b32_e32 v21, 1, v20
	v_add3_u32 v254, v254, v20, v21
	v_permlane16_swap_b32_e32 v250, v252
	v_permlane16_swap_b32_e32 v251, v253
	buffer_store_dwordx4 v[250:253], v254, s[24:27], 0 offen sc1
.LBB0_754:
	v_or_b32_e32 v19, 0x80, v18
	v_pk_mul_f32 v[6:7], s[18:19], v[6:7]
	v_pk_mul_f32 v[4:5], s[16:17], v[4:5]
	s_andn2_b64 vcc, exec, s[10:11]
	s_mov_b64 s[72:73], -1
	s_cbranch_vccnz .Ler_f23
	v_lshlrev_b32_e32 v254, 1, v19
	v_cvt_pk_bf16_f32 v250, v4, v5
	v_cvt_pk_bf16_f32 v251, v6, v7
